# attention PV (first q-block): 4 V-fragment ds_read2 in flight with counted lgkmcnt instead of read-wait-mfma chain
# baseline (speedup 1.0000x reference)
; #define LAS __attribute__((address_space(3)))
; __device__ __forceinline__ void attn_unit(LAS unsigned char* lds, bf16_t* Y, const bf16_t* KB, const bf16_t* VT, const float* sink, int b, int kvh, int qb, bool isctx) {
;     ...
; #pragma unroll
;             for (int d = 0; d < 2; ++d)
; #pragma unroll
;                 for (int kk = 0; kk < 4; ++kk) { const int kb = kk >> 1, jj = kk & 1;
;                     const LAS unsigned char* vp = Vs + ((32 * d + r32) * 72 + 32 * kb + 16 * jj + 4 * hi) * 2;
;                     const u32x2 lo = *(const LAS u32x2*)vp, hh = *(const LAS u32x2*)(vp + 16);
;                     const u32x4 w = {lo.x, lo.y, hh.x, hh.y}; const bf16x8 vf = __builtin_bit_cast(bf16x8, w);
;                     o[j][d] = __builtin_amdgcn_mfma_f32_32x32x16_bf16(vf, pf[kk], o[j][d], 0, 0, 0); }
.LBB0_256:
	v_max_f32_e32 v173, v81, v81
	v_max_f32_e32 v174, v80, v80
	v_max_f32_e32 v173, v174, v173
	v_max3_f32 v173, v173, v82, v83
	v_max3_f32 v173, v173, v84, v85
	v_max3_f32 v173, v173, v86, v87
	v_max3_f32 v173, v173, v88, v89
	v_max3_f32 v173, v173, v90, v91
	v_max3_f32 v173, v173, v92, v93
	v_max3_f32 v173, v173, v94, v95
	v_max3_f32 v173, v173, v64, v65
	v_max3_f32 v173, v173, v66, v67
	v_max3_f32 v173, v173, v68, v69
	v_max3_f32 v173, v173, v70, v71
	v_max3_f32 v173, v173, v72, v73
	v_max3_f32 v173, v173, v74, v75
	v_max3_f32 v173, v173, v76, v77
	v_max3_f32 v173, v173, v78, v79
	ds_bpermute_b32 v174, v149, v173
	v_add_u32_e32 v176, s67, v140
	s_andn2_b64 vcc, exec, s[46:47]
	s_waitcnt lgkmcnt(0)
	v_max3_f32 v173, v148, v173, v174
	v_sub_f32_e32 v80, v80, v173
	v_sub_f32_e32 v64, v64, v173
	v_exp_f32_e32 v179, v80
	v_sub_f32_e32 v80, v81, v173
	v_exp_f32_e32 v199, v64
	v_sub_f32_e32 v64, v65, v173
	v_exp_f32_e32 v181, v80
	v_sub_f32_e32 v80, v82, v173
	v_exp_f32_e32 v200, v64
	v_sub_f32_e32 v64, v66, v173
	v_exp_f32_e32 v183, v80
	v_sub_f32_e32 v80, v83, v173
	v_exp_f32_e32 v201, v64
	v_sub_f32_e32 v64, v67, v173
	v_exp_f32_e32 v185, v80
	v_sub_f32_e32 v80, v84, v173
	v_exp_f32_e32 v202, v64
	v_sub_f32_e32 v64, v68, v173
	v_exp_f32_e32 v187, v80
	v_sub_f32_e32 v80, v85, v173
	v_exp_f32_e32 v203, v64
	v_sub_f32_e32 v64, v69, v173
	v_exp_f32_e32 v188, v80
	v_sub_f32_e32 v80, v86, v173
	v_exp_f32_e32 v204, v64
	v_sub_f32_e32 v64, v70, v173
	v_exp_f32_e32 v189, v80
	v_sub_f32_e32 v80, v87, v173
	v_exp_f32_e32 v205, v64
	v_sub_f32_e32 v64, v71, v173
	v_exp_f32_e32 v190, v80
	v_sub_f32_e32 v80, v88, v173
	v_exp_f32_e32 v206, v64
	v_sub_f32_e32 v64, v72, v173
	v_exp_f32_e32 v191, v80
	v_sub_f32_e32 v80, v89, v173
	v_exp_f32_e32 v207, v64
	v_sub_f32_e32 v64, v73, v173
	v_exp_f32_e32 v192, v80
	v_sub_f32_e32 v80, v90, v173
	v_exp_f32_e32 v212, v64
	v_sub_f32_e32 v64, v74, v173
	v_exp_f32_e32 v193, v80
	v_sub_f32_e32 v80, v91, v173
	v_exp_f32_e32 v213, v64
	v_sub_f32_e32 v64, v75, v173
	v_exp_f32_e32 v194, v80
	v_sub_f32_e32 v80, v92, v173
	v_exp_f32_e32 v180, v64
	v_sub_f32_e32 v64, v76, v173
	v_exp_f32_e32 v195, v80
	v_sub_f32_e32 v80, v93, v173
	v_exp_f32_e32 v182, v64
	v_sub_f32_e32 v64, v77, v173
	v_sub_f32_e32 v148, v148, v173
	v_exp_f32_e32 v196, v80
	v_sub_f32_e32 v80, v94, v173
	v_exp_f32_e32 v184, v64
	v_sub_f32_e32 v64, v78, v173
	v_add_u32_e32 v88, v176, v153
	v_exp_f32_e32 v197, v80
	v_sub_f32_e32 v80, v95, v173
	v_exp_f32_e32 v186, v64
	v_sub_f32_e32 v64, v79, v173
	v_exp_f32_e32 v148, v148
	v_add_u32_e32 v176, 0x2000, v88
	v_exp_f32_e32 v198, v80
	v_exp_f32_e32 v174, v64
	v_cvt_pk_bf16_f32 v64, v179, v181
	v_cvt_pk_bf16_f32 v65, v183, v185
	v_cvt_pk_bf16_f32 v66, v187, v188
	v_cvt_pk_bf16_f32 v67, v189, v190
	v_cvt_pk_bf16_f32 v68, v191, v192
	v_cvt_pk_bf16_f32 v69, v193, v194
	v_cvt_pk_bf16_f32 v70, v195, v196
	v_cvt_pk_bf16_f32 v71, v197, v198
	v_cvt_pk_bf16_f32 v72, v199, v200
	v_cvt_pk_bf16_f32 v73, v201, v202
	v_cvt_pk_bf16_f32 v74, v203, v204
	v_cvt_pk_bf16_f32 v75, v205, v206
	v_cvt_pk_bf16_f32 v76, v207, v212
	v_cvt_pk_bf16_f32 v77, v213, v180
	v_cvt_pk_bf16_f32 v78, v182, v184
	v_cvt_pk_bf16_f32 v79, v186, v174
	v_add_u32_e32 v177, 0x3000, v88
	ds_read2_b64 v[80:83], v176 offset0:128 offset1:130
	ds_read2_b64 v[84:87], v176 offset0:132 offset1:134
	ds_read2_b64 v[88:91], v176 offset0:136 offset1:138
	ds_read2_b64 v[92:95], v176 offset0:140 offset1:142
	v_pk_mul_f32 v[62:63], v[62:63], v[148:149] op_sel_hi:[1,0]
	v_pk_mul_f32 v[60:61], v[60:61], v[148:149] op_sel_hi:[1,0]
	v_pk_mul_f32 v[58:59], v[58:59], v[148:149] op_sel_hi:[1,0]
	v_pk_mul_f32 v[56:57], v[56:57], v[148:149] op_sel_hi:[1,0]
	v_pk_mul_f32 v[54:55], v[54:55], v[148:149] op_sel_hi:[1,0]
	v_pk_mul_f32 v[52:53], v[52:53], v[148:149] op_sel_hi:[1,0]
	v_pk_mul_f32 v[50:51], v[50:51], v[148:149] op_sel_hi:[1,0]
	v_pk_mul_f32 v[48:49], v[48:49], v[148:149] op_sel_hi:[1,0]
	v_pk_mul_f32 v[46:47], v[46:47], v[148:149] op_sel_hi:[1,0]
	s_waitcnt lgkmcnt(3)
	v_mfma_f32_32x32x16_bf16 v[48:63], v[80:83], v[64:67], v[48:63]
	ds_read2_b64 v[80:83], v177 offset0:192 offset1:194
	v_mul_f32_e64 v44, v44, v148
	v_mul_f32_e64 v45, v45, v148
	v_mul_f32_e64 v42, v42, v148
	v_mul_f32_e64 v43, v43, v148
	v_pk_mul_f32 v[40:41], v[40:41], v[148:149] op_sel_hi:[1,0]
	v_pk_mul_f32 v[38:39], v[38:39], v[148:149] op_sel_hi:[1,0]
	v_pk_mul_f32 v[36:37], v[36:37], v[148:149] op_sel_hi:[1,0]
	v_pk_mul_f32 v[34:35], v[34:35], v[148:149] op_sel_hi:[1,0]
	s_waitcnt lgkmcnt(3)
	v_mfma_f32_32x32x16_bf16 v[48:63], v[84:87], v[68:71], v[48:63]
	ds_read2_b64 v[84:87], v177 offset0:196 offset1:198
	v_mul_f32_e64 v32, v32, v148
	v_mul_f32_e64 v33, v33, v148
	s_waitcnt lgkmcnt(3)
	v_mfma_f32_32x32x16_bf16 v[48:63], v[88:91], v[72:75], v[48:63]
	ds_read2_b64 v[88:91], v177 offset0:200 offset1:202
	s_waitcnt lgkmcnt(3)
	v_mfma_f32_32x32x16_bf16 v[48:63], v[92:95], v[76:79], v[48:63]
	ds_read2_b64 v[92:95], v177 offset0:204 offset1:206
	s_waitcnt lgkmcnt(3)
	v_mfma_f32_32x32x16_bf16 v[32:47], v[80:83], v[64:67], v[32:47]
	s_waitcnt lgkmcnt(2)
	v_mfma_f32_32x32x16_bf16 v[32:47], v[84:87], v[68:71], v[32:47]
	s_waitcnt lgkmcnt(1)
	v_mfma_f32_32x32x16_bf16 v[32:47], v[88:91], v[72:75], v[32:47]
	s_waitcnt lgkmcnt(0)
	v_mfma_f32_32x32x16_bf16 v[32:47], v[92:95], v[76:79], v[32:47]
	ds_read_b128 v[64:67], v178
	ds_read_b128 v[68:71], v178 offset:32
	ds_read_b128 v[218:221], v178 offset:4704
	s_waitcnt lgkmcnt(2)
	v_mfma_f32_32x32x16_bf16 v[80:95], v[64:67], v[112:115], 0
	s_waitcnt lgkmcnt(1)
	v_mfma_f32_32x32x16_bf16 v[80:95], v[68:71], v[116:119], v[80:95]
	v_mfma_f32_32x32x16_bf16 v[80:95], v[222:225], v[120:123], v[80:95]
	v_mfma_f32_32x32x16_bf16 v[80:95], v[226:229], v[124:127], v[80:95]
	v_mfma_f32_32x32x16_bf16 v[64:79], v[230:233], v[112:115], 0
	v_mfma_f32_32x32x16_bf16 v[64:79], v[234:237], v[116:119], v[64:79]
	v_mfma_f32_32x32x16_bf16 v[64:79], v[246:249], v[120:123], v[64:79]
	s_waitcnt lgkmcnt(0)
	v_mfma_f32_32x32x16_bf16 v[64:79], v[218:221], v[124:127], v[64:79]
	s_cbranch_vccnz .LBB0_258
; __device__ __forceinline__ int crow(int r, int hi) { return (r & 3) + 8 * (r >> 2) + 4 * hi; }
; __device__ __forceinline__ void attn_unit(LAS unsigned char* lds, bf16_t* Y, const bf16_t* KB, const bf16_t* VT, const float* sink, int b, int kvh, int qb, bool isctx) {
;     ...
;             if (it < ntl) { const int ks0 = qb * 128 - 128 + 64 * it;
; #pragma unroll
;                 for (int kb = 0; kb < 2; ++kb)
; #pragma unroll
;                     for (int r = 0; r < 16; ++r) { const int dk = (tq0 + 32 * j + r32) - (ks0 + 32 * kb + crow(r, hi)); if (dk > 128 || dk < -128) s[kb][r] = -1e30f; } }
	v_readfirstlane_b32 s98, v242
	s_bfe_u32 s98, s98, 0x10006
	s_sub_i32 s99, s66, s98
	s_add_i32 s99, s99, -1
	s_cmp_lt_u32 s99, 3
	s_cbranch_scc1 .LBB0_258
	v_subrev_u32_e32 v178, s63, v171
	v_add_u32_e32 v210, v178, v152
	v_cmp_gt_u32_e32 vcc, s94, v210
	v_add_u32_e32 v210, v178, v154
	s_nop 0
	v_cndmask_b32_e32 v80, v80, v245, vcc
	v_cmp_lt_u32_e32 vcc, s20, v210
	v_add_u32_e32 v210, v178, v155
	s_nop 0
	v_cndmask_b32_e32 v81, v245, v81, vcc
	v_cmp_lt_u32_e32 vcc, s20, v210
	v_add_u32_e32 v210, v178, v156
	s_nop 0
	v_cndmask_b32_e32 v82, v245, v82, vcc
	v_cmp_lt_u32_e32 vcc, s20, v210
	v_add_u32_e32 v210, v178, v157
	s_nop 0
	v_cndmask_b32_e32 v83, v245, v83, vcc
	v_cmp_lt_u32_e32 vcc, s20, v210
	v_add_u32_e32 v210, v178, v158
	s_nop 0
	v_cndmask_b32_e32 v84, v245, v84, vcc
	v_cmp_lt_u32_e32 vcc, s20, v210
	v_add_u32_e32 v210, v178, v159
	s_nop 0
	v_cndmask_b32_e32 v85, v245, v85, vcc
	v_cmp_lt_u32_e32 vcc, s20, v210
	v_add_u32_e32 v210, v178, v160
	s_nop 0
	v_cndmask_b32_e32 v86, v245, v86, vcc
	v_cmp_lt_u32_e32 vcc, s20, v210
	v_add_u32_e32 v210, v178, v161
	s_nop 0
	v_cndmask_b32_e32 v87, v245, v87, vcc
	v_cmp_lt_u32_e32 vcc, s20, v210
	v_add_u32_e32 v210, v178, v162
	s_nop 0
	v_cndmask_b32_e32 v88, v245, v88, vcc
	v_cmp_lt_u32_e32 vcc, s20, v210
	v_add_u32_e32 v210, v178, v163
	s_nop 0
	v_cndmask_b32_e32 v89, v245, v89, vcc
	v_cmp_lt_u32_e32 vcc, s20, v210
	v_add_u32_e32 v210, v178, v164
	s_nop 0
	v_cndmask_b32_e32 v90, v245, v90, vcc
	v_cmp_lt_u32_e32 vcc, s20, v210
	v_add_u32_e32 v210, v178, v165
	s_nop 0
	v_cndmask_b32_e32 v91, v245, v91, vcc
	v_cmp_lt_u32_e32 vcc, s20, v210
	v_add_u32_e32 v210, v178, v166
	s_nop 0
	v_cndmask_b32_e32 v92, v245, v92, vcc
	v_cmp_lt_u32_e32 vcc, s20, v210
	v_add_u32_e32 v210, v178, v167
	v_add_u32_e32 v178, v178, v168
	v_cndmask_b32_e32 v93, v245, v93, vcc
	v_cmp_lt_u32_e32 vcc, s20, v210
	s_nop 1
	v_cndmask_b32_e32 v94, v245, v94, vcc
	v_cmp_lt_u32_e32 vcc, s20, v178
	v_add_u32_e32 v178, v175, v152
	s_nop 0
	v_cndmask_b32_e32 v95, v245, v95, vcc
	v_cmp_lt_u32_e32 vcc, s20, v178
	v_add_u32_e32 v178, v175, v154
	s_nop 0
	v_cndmask_b32_e32 v64, v245, v64, vcc
	v_cmp_lt_u32_e32 vcc, s20, v178
	v_add_u32_e32 v178, v175, v155
	s_nop 0
	v_cndmask_b32_e32 v65, v245, v65, vcc
	v_cmp_lt_u32_e32 vcc, s20, v178
	v_add_u32_e32 v178, v175, v156
	s_nop 0
	v_cndmask_b32_e32 v66, v245, v66, vcc
	v_cmp_lt_u32_e32 vcc, s20, v178
	v_add_u32_e32 v178, v175, v157
	s_nop 0
	v_cndmask_b32_e32 v67, v245, v67, vcc
	v_cmp_lt_u32_e32 vcc, s20, v178
	v_add_u32_e32 v178, v175, v158
	s_nop 0
	v_cndmask_b32_e32 v68, v245, v68, vcc
	v_cmp_lt_u32_e32 vcc, s20, v178
	v_add_u32_e32 v178, v175, v159
	s_nop 0
	v_cndmask_b32_e32 v69, v245, v69, vcc
	v_cmp_lt_u32_e32 vcc, s20, v178
	v_add_u32_e32 v178, v175, v160
	s_nop 0
	v_cndmask_b32_e32 v70, v245, v70, vcc
	v_cmp_lt_u32_e32 vcc, s20, v178
	v_add_u32_e32 v178, v175, v161
	s_nop 0
	v_cndmask_b32_e32 v71, v245, v71, vcc
	v_cmp_lt_u32_e32 vcc, s20, v178
	v_add_u32_e32 v178, v175, v162
	s_nop 0
	v_cndmask_b32_e32 v72, v245, v72, vcc
	v_cmp_lt_u32_e32 vcc, s20, v178
	v_add_u32_e32 v178, v175, v163
	s_nop 0
	v_cndmask_b32_e32 v73, v245, v73, vcc
	v_cmp_lt_u32_e32 vcc, s20, v178
	v_add_u32_e32 v178, v175, v164
	s_nop 0
	v_cndmask_b32_e32 v74, v245, v74, vcc
	v_cmp_lt_u32_e32 vcc, s20, v178
	v_add_u32_e32 v178, v175, v165
	s_nop 0
	v_cndmask_b32_e32 v75, v245, v75, vcc
	v_cmp_lt_u32_e32 vcc, s20, v178
	v_add_u32_e32 v178, v175, v166
	s_nop 0
	v_cndmask_b32_e32 v76, v245, v76, vcc
	v_cmp_lt_u32_e32 vcc, s20, v178
	v_add_u32_e32 v178, v175, v167
	v_add_u32_e32 v175, v175, v168
	v_cndmask_b32_e32 v77, v245, v77, vcc
	v_cmp_lt_u32_e32 vcc, s20, v178
	s_nop 1
	v_cndmask_b32_e32 v78, v245, v78, vcc
	v_cmp_lt_u32_e32 vcc, s20, v175
	s_nop 1
	v_cndmask_b32_e32 v79, v245, v79, vcc
